# grid barrier: XGEN release issued without waiting for the TOPGEN atomic
# baseline (speedup 1.0000x reference)
.LBB0_156:
	s_or_b64 exec, exec, s[36:37]
	global_atomic_add v[174:175], v190, off
	s_waitcnt vmcnt(0)
	buffer_inv sc1
	s_waitcnt vmcnt(0)

.LBB0_431:
	s_or_b64 exec, exec, s[38:39]
	global_atomic_add v[174:175], v190, off
	s_waitcnt vmcnt(0)
	buffer_inv sc1
	s_waitcnt vmcnt(0)

.LBB0_942:
	s_or_b64 exec, exec, s[40:41]
	global_atomic_add v[174:175], v190, off
	s_waitcnt vmcnt(0)
	buffer_inv sc1
	s_waitcnt vmcnt(0)
